# UG GEMM K-loop: the compiler's vmcnt(0) drain at the loop head moved to the loop entry (tile loads stay in flight across iterations)
# speedup vs baseline: 1.0014x; 1.0001x over previous
; #define PG8_STAGE(bufoff, gbase, voff) do { _Pragma("unroll") for (int _i = 0; _i < 2; ++_i) \
;         __builtin_amdgcn_global_load_lds((const unsigned*)((const char*)(gbase) + (voff)[_i]), (PG8_LAS unsigned*)(lds + (bufoff) + ldsw + _i * 8192), 16, 0, 0); } while (0)
; #define PG8_LDA(dst, b, h) do { _Pragma("unroll") for (int m = 0; m < 4; ++m) _Pragma("unroll") for (int k = 0; k < 2; ++k) dst[m][k] = *(const PG8_LAS bf16x8*)(lds + PG8_SA(b, h) + aoff + m * 2048 + k * 1024); } while (0)
; #define PG8_LDB(dst, b, h) do { _Pragma("unroll") for (int n = 0; n < 2; ++n) _Pragma("unroll") for (int k = 0; k < 2; ++k) dst[n][k] = *(const PG8_LAS bf16x8*)(lds + PG8_SB(b, h) + boff + n * 2048 + k * 1024); } while (0)
; #define PG8_MMA(ai, bj, At, Bt) do { __builtin_amdgcn_s_setprio(1); _Pragma("unroll") for (int m = 0; m < 4; ++m) _Pragma("unroll") for (int n = 0; n < 2; ++n) _Pragma("unroll") for (int k = 0; k < 2; ++k) \
;         acc[ai][bj][m][n] = __builtin_amdgcn_mfma_f32_16x16x32_bf16(Bt[n][k], At[m][k], acc[ai][bj][m][n], 0, 0, 0); __builtin_amdgcn_s_setprio(0); } while (0)
; #define PG8_BAR __builtin_amdgcn_s_barrier()
; template <class Epi, class Sched, bool ALIGN_EPI = false, bool SP2 = false>
; __device__ __forceinline__ void gemm_phase(PG8_LAS unsigned char* lds, const Gemm g, const Sched& S, const Epi& E, int tid_in) {
;     ...
;         for (int t = 0; t < ntc; t += 2) {
;             const bool last = (t == ntc - 2);
;             const char* a1 = PG8_KA(cA, t + 1);
;             const char* a2 = last ? nA : PG8_KA(cA, t + 2); const char* b2 = last ? nB : cB + (size_t)(t + 2) * kstep;
;             const char* a3 = last ? PG8_KA(nA, 1) : PG8_KA(cA, t + 3); const char* b3 = b2 + kstep;
;             if (last && has_next) S.a_ready(nxt);
;             if constexpr (SP2) {
;             PG8_LDB(B0, 0, 0); PG8_LDB(B1, 0, 1); PG8_SCHED; PG8_LDA(At, 0, 0); PG8_STAGE(PG8_SA(1, 1), a1 + hstepA, voffA);
;             PG8_WAIT_V(8); PG8_WAIT_L(0); PG8_BAR; PG8_MMA(0, 0, At, B0); PG8_MMA(0, 1, At, B1); PG8_BAR; PG8_SCHED;
;     ...
;         for (int a = 0; a < 2; ++a)
; #pragma unroll
;             for (int b = 0; b < 2; ++b)
; #pragma unroll
;                 for (int m = 0; m < 4; ++m)
; #pragma unroll
;                     for (int n = 0; n < 2; ++n) acc[a][b][m][n] = (f32x4){0.f, 0.f, 0.f, 0.f};
;         cur = nxt; cA = nA; cB = nB; ++ui; ntc = PG8_KNT(cur.pn);
.LBB0_1179:
	s_add_u32 s21, s48, 0x80
	s_addc_u32 s53, s49, 0
	s_add_u32 s54, s8, 0x100
	v_mov_b32_e32 v8, 0
	s_addc_u32 s55, s9, 0
	s_mov_b32 s0, 0
	s_mov_b32 s56, s79
	v_mov_b32_e32 v9, v8
	v_mov_b32_e32 v10, v8
	v_mov_b32_e32 v11, v8
	v_mov_b32_e32 v16, v8
	v_mov_b32_e32 v17, v8
	v_mov_b32_e32 v18, v8
	v_mov_b32_e32 v19, v8
	v_mov_b32_e32 v24, v8
	v_mov_b32_e32 v25, v8
	v_mov_b32_e32 v26, v8
	v_mov_b32_e32 v27, v8
	v_mov_b32_e32 v32, v8
	v_mov_b32_e32 v33, v8
	v_mov_b32_e32 v34, v8
	v_mov_b32_e32 v35, v8
	v_mov_b32_e32 v40, v8
	v_mov_b32_e32 v41, v8
	v_mov_b32_e32 v42, v8
	v_mov_b32_e32 v43, v8
	v_mov_b32_e32 v48, v8
	v_mov_b32_e32 v49, v8
	v_mov_b32_e32 v50, v8
	v_mov_b32_e32 v51, v8
	v_mov_b32_e32 v56, v8
	v_mov_b32_e32 v57, v8
	v_mov_b32_e32 v58, v8
	v_mov_b32_e32 v59, v8
	v_mov_b32_e32 v64, v8
	v_mov_b32_e32 v65, v8
	v_mov_b32_e32 v66, v8
	v_mov_b32_e32 v67, v8
	v_mov_b32_e32 v4, v8
	v_mov_b32_e32 v5, v8
	v_mov_b32_e32 v6, v8
	v_mov_b32_e32 v7, v8
	v_mov_b32_e32 v12, v8
	v_mov_b32_e32 v13, v8
	v_mov_b32_e32 v14, v8
	v_mov_b32_e32 v15, v8
	v_mov_b32_e32 v20, v8
	v_mov_b32_e32 v21, v8
	v_mov_b32_e32 v22, v8
	v_mov_b32_e32 v23, v8
	v_mov_b32_e32 v28, v8
	v_mov_b32_e32 v29, v8
	v_mov_b32_e32 v30, v8
	v_mov_b32_e32 v31, v8
	v_mov_b32_e32 v36, v8
	v_mov_b32_e32 v37, v8
	v_mov_b32_e32 v38, v8
	v_mov_b32_e32 v39, v8
	v_mov_b32_e32 v44, v8
	v_mov_b32_e32 v45, v8
	v_mov_b32_e32 v46, v8
	v_mov_b32_e32 v47, v8
	v_mov_b32_e32 v52, v8
	v_mov_b32_e32 v53, v8
	v_mov_b32_e32 v54, v8
	v_mov_b32_e32 v55, v8
	v_mov_b32_e32 v60, v8
	v_mov_b32_e32 v61, v8
	v_mov_b32_e32 v62, v8
	v_mov_b32_e32 v63, v8
	v_mov_b32_e32 v72, v8
	v_mov_b32_e32 v73, v8
	v_mov_b32_e32 v74, v8
	v_mov_b32_e32 v75, v8
	v_mov_b32_e32 v80, v8
	v_mov_b32_e32 v81, v8
	v_mov_b32_e32 v82, v8
	v_mov_b32_e32 v83, v8
	v_mov_b32_e32 v88, v8
	v_mov_b32_e32 v89, v8
	v_mov_b32_e32 v90, v8
	v_mov_b32_e32 v91, v8
	v_mov_b32_e32 v96, v8
	v_mov_b32_e32 v97, v8
	v_mov_b32_e32 v98, v8
	v_mov_b32_e32 v99, v8
	v_mov_b32_e32 v104, v8
	v_mov_b32_e32 v105, v8
	v_mov_b32_e32 v106, v8
	v_mov_b32_e32 v107, v8
	v_mov_b32_e32 v112, v8
	v_mov_b32_e32 v113, v8
	v_mov_b32_e32 v114, v8
	v_mov_b32_e32 v115, v8
	v_mov_b32_e32 v120, v8
	v_mov_b32_e32 v121, v8
	v_mov_b32_e32 v122, v8
	v_mov_b32_e32 v123, v8
	v_mov_b32_e32 v128, v8
	v_mov_b32_e32 v129, v8
	v_mov_b32_e32 v130, v8
	v_mov_b32_e32 v131, v8
	v_mov_b32_e32 v68, v8
	v_mov_b32_e32 v69, v8
	v_mov_b32_e32 v70, v8
	v_mov_b32_e32 v71, v8
	v_mov_b32_e32 v76, v8
	v_mov_b32_e32 v77, v8
	v_mov_b32_e32 v78, v8
	v_mov_b32_e32 v79, v8
	v_mov_b32_e32 v84, v8
	v_mov_b32_e32 v85, v8
	v_mov_b32_e32 v86, v8
	v_mov_b32_e32 v87, v8
	v_mov_b32_e32 v92, v8
	v_mov_b32_e32 v93, v8
	v_mov_b32_e32 v94, v8
	v_mov_b32_e32 v95, v8
	v_mov_b32_e32 v100, v8
	v_mov_b32_e32 v101, v8
	v_mov_b32_e32 v102, v8
	v_mov_b32_e32 v103, v8
	v_mov_b32_e32 v108, v8
	v_mov_b32_e32 v109, v8
	v_mov_b32_e32 v110, v8
	v_mov_b32_e32 v111, v8
	v_mov_b32_e32 v116, v8
	v_mov_b32_e32 v117, v8
	v_mov_b32_e32 v118, v8
	v_mov_b32_e32 v119, v8
	v_mov_b32_e32 v124, v8
	v_mov_b32_e32 v125, v8
	v_mov_b32_e32 v126, v8
	v_mov_b32_e32 v127, v8
	s_waitcnt vmcnt(0)
.LBB0_1180:
	s_or_b32 s1, s0, 1
	s_cmp_ge_u32 s1, s84
	s_cselect_b32 s58, s86, 0
	s_cselect_b32 s59, s85, 0
	s_add_i32 s57, s0, 2
	s_cmp_ge_u32 s57, s84
	s_cselect_b32 s8, s86, 0
	s_cselect_b32 s1, s85, 0
	s_add_u32 s8, s6, s8
	s_addc_u32 s1, s7, s1
	s_add_u32 s8, s8, 0x100
	s_addc_u32 s1, s1, 0
	s_add_i32 s0, s0, 3
	s_cmp_ge_u32 s0, s84
	s_cselect_b32 s9, s86, 0
	s_cselect_b32 s0, s85, 0
	s_add_u32 s9, s6, s9
	s_addc_u32 s0, s7, s0
	s_add_u32 s62, s9, 0x180
	s_addc_u32 s0, s0, 0
	s_cmp_eq_u32 s56, 0
	s_cselect_b32 s9, s49, s1
	s_cselect_b32 s8, s48, s8
	s_cselect_b32 s61, s51, s55
	s_cselect_b32 s60, s50, s54
	s_cselect_b32 s1, s53, s0
	s_cselect_b32 s0, s21, s62
	s_add_i32 s62, 0, 0x10000
	v_add_u32_e32 v0, s62, v207
	s_add_i32 s63, 0, 0x14000
	ds_read_b128 v[132:135], v0
	ds_read_b128 v[136:139], v0 offset:1024
	ds_read_b128 v[140:143], v0 offset:2048
	ds_read_b128 v[144:147], v0 offset:3072
	v_add_u32_e32 v0, s63, v207
	ds_read_b128 v[148:151], v0
	ds_read_b128 v[152:155], v0 offset:1024
	ds_read_b128 v[156:159], v0 offset:2048
	ds_read_b128 v[160:163], v0 offset:3072
	v_lshl_add_u64 v[2:3], s[6:7], 0, v[180:181]
	v_lshl_add_u64 v[2:3], v[2:3], 0, s[58:59]
	s_add_i32 m0, s89, 0xc000
	ds_read_b128 v[164:167], v208
	ds_read_b128 v[168:171], v208 offset:1024
	ds_read_b128 v[184:187], v208 offset:2048
	ds_read_b128 v[188:191], v208 offset:3072
	ds_read_b128 v[196:199], v208 offset:4096
	ds_read_b128 v[200:203], v208 offset:5120
	ds_read_b128 v[210:213], v208 offset:6144
	ds_read_b128 v[214:217], v208 offset:7168
	global_load_lds_dwordx4 v[2:3], off
	v_lshl_add_u64 v[2:3], s[6:7], 0, v[182:183]
	v_lshl_add_u64 v[2:3], v[2:3], 0, s[58:59]
	s_add_i32 m0, s89, 0xe000
	s_nop 0
	global_load_lds_dwordx4 v[2:3], off
	s_waitcnt vmcnt(8)
	s_waitcnt lgkmcnt(0)
	s_barrier
; #define PG8_STAGE(bufoff, gbase, voff) do { _Pragma("unroll") for (int _i = 0; _i < 2; ++_i) \
;         __builtin_amdgcn_global_load_lds((const unsigned*)((const char*)(gbase) + (voff)[_i]), (PG8_LAS unsigned*)(lds + (bufoff) + ldsw + _i * 8192), 16, 0, 0); } while (0)
; #define PG8_LDA(dst, b, h) do { _Pragma("unroll") for (int m = 0; m < 4; ++m) _Pragma("unroll") for (int k = 0; k < 2; ++k) dst[m][k] = *(const PG8_LAS bf16x8*)(lds + PG8_SA(b, h) + aoff + m * 2048 + k * 1024); } while (0)
; #define PG8_MMA(ai, bj, At, Bt) do { __builtin_amdgcn_s_setprio(1); _Pragma("unroll") for (int m = 0; m < 4; ++m) _Pragma("unroll") for (int n = 0; n < 2; ++n) _Pragma("unroll") for (int k = 0; k < 2; ++k) \
;         acc[ai][bj][m][n] = __builtin_amdgcn_mfma_f32_16x16x32_bf16(Bt[n][k], At[m][k], acc[ai][bj][m][n], 0, 0, 0); __builtin_amdgcn_s_setprio(0); } while (0)
; #define PG8_WAIT_V(n) asm volatile("s_waitcnt vmcnt(" #n ")" ::: "memory")
; #define PG8_WAIT_L(n) asm volatile("s_waitcnt lgkmcnt(" #n ")" ::: "memory")
; #define PG8_BAR __builtin_amdgcn_s_barrier()
; #define PG8_SCHED __builtin_amdgcn_sched_barrier(0)
; template <class Epi, class Sched, bool ALIGN_EPI = false, bool SP2 = false>
; __device__ __forceinline__ void gemm_phase(PG8_LAS unsigned char* lds, const Gemm g, const Sched& S, const Epi& E, int tid_in) {
;     ...
;             PG8_WAIT_V(8); PG8_WAIT_L(0); PG8_BAR; PG8_MMA(0, 0, At, B0); PG8_MMA(0, 1, At, B1); PG8_BAR; PG8_SCHED;
;             PG8_LDA(At, 0, 1); PG8_STAGE(PG8_SB(0, 0), b2, voffB); PG8_STAGE(PG8_SB(0, 1), b2 + hstep, voffB); PG8_STAGE(PG8_SA(0, 0), a2, voffA);
;             PG8_WAIT_V(8); PG8_WAIT_L(0); PG8_BAR; PG8_MMA(1, 0, At, B0); PG8_MMA(1, 1, At, B1); PG8_BAR; PG8_SCHED;
	s_setprio 1
	s_waitcnt lgkmcnt(0)
	v_mfma_f32_16x16x32_bf16 v[124:127], v[132:135], v[164:167], v[124:127]
	v_mfma_f32_16x16x32_bf16 v[116:119], v[140:143], v[164:167], v[116:119]
	v_mfma_f32_16x16x32_bf16 v[108:111], v[132:135], v[184:187], v[108:111]
	v_mfma_f32_16x16x32_bf16 v[100:103], v[140:143], v[184:187], v[100:103]
	v_mfma_f32_16x16x32_bf16 v[92:95], v[132:135], v[196:199], v[92:95]
	v_mfma_f32_16x16x32_bf16 v[84:87], v[140:143], v[196:199], v[84:87]
	v_mfma_f32_16x16x32_bf16 v[76:79], v[132:135], v[210:213], v[76:79]
	v_mfma_f32_16x16x32_bf16 v[68:71], v[140:143], v[210:213], v[68:71]
	v_mfma_f32_16x16x32_bf16 v[124:127], v[136:139], v[168:171], v[124:127]
	v_mfma_f32_16x16x32_bf16 v[116:119], v[144:147], v[168:171], v[116:119]
	v_mfma_f32_16x16x32_bf16 v[108:111], v[136:139], v[188:191], v[108:111]
	v_mfma_f32_16x16x32_bf16 v[100:103], v[144:147], v[188:191], v[100:103]
	v_mfma_f32_16x16x32_bf16 v[92:95], v[136:139], v[200:203], v[92:95]
	v_mfma_f32_16x16x32_bf16 v[84:87], v[144:147], v[200:203], v[84:87]
	v_mfma_f32_16x16x32_bf16 v[76:79], v[136:139], v[214:217], v[76:79]
	v_mfma_f32_16x16x32_bf16 v[68:71], v[144:147], v[214:217], v[68:71]
	s_setprio 0
	s_setprio 1
	v_mfma_f32_16x16x32_bf16 v[128:131], v[148:151], v[164:167], v[128:131]
	v_mfma_f32_16x16x32_bf16 v[120:123], v[156:159], v[164:167], v[120:123]
	v_mfma_f32_16x16x32_bf16 v[112:115], v[148:151], v[184:187], v[112:115]
	v_mfma_f32_16x16x32_bf16 v[104:107], v[156:159], v[184:187], v[104:107]
	v_mfma_f32_16x16x32_bf16 v[96:99], v[148:151], v[196:199], v[96:99]
	v_mfma_f32_16x16x32_bf16 v[88:91], v[156:159], v[196:199], v[88:91]
	v_mfma_f32_16x16x32_bf16 v[80:83], v[148:151], v[210:213], v[80:83]
	v_mfma_f32_16x16x32_bf16 v[72:75], v[156:159], v[210:213], v[72:75]
	v_mfma_f32_16x16x32_bf16 v[128:131], v[152:155], v[168:171], v[128:131]
	v_mfma_f32_16x16x32_bf16 v[120:123], v[160:163], v[168:171], v[120:123]
	v_mfma_f32_16x16x32_bf16 v[112:115], v[152:155], v[188:191], v[112:115]
	v_mfma_f32_16x16x32_bf16 v[104:107], v[160:163], v[188:191], v[104:107]
	v_mfma_f32_16x16x32_bf16 v[96:99], v[152:155], v[200:203], v[96:99]
	v_mfma_f32_16x16x32_bf16 v[88:91], v[160:163], v[200:203], v[88:91]
	v_mfma_f32_16x16x32_bf16 v[80:83], v[152:155], v[214:217], v[80:83]
	v_mfma_f32_16x16x32_bf16 v[72:75], v[160:163], v[214:217], v[72:75]
	s_setprio 0
	s_barrier
	s_add_i32 s58, s62, s88
	v_lshl_add_u64 v[192:193], s[60:61], 0, v[178:179]
	s_mov_b32 m0, s58
	ds_read_b128 v[164:167], v208 offset:16384
	ds_read_b128 v[168:171], v208 offset:17408
	ds_read_b128 v[184:187], v208 offset:18432
	ds_read_b128 v[188:191], v208 offset:19456
	ds_read_b128 v[196:199], v208 offset:20480
	ds_read_b128 v[200:203], v208 offset:21504
	ds_read_b128 v[210:213], v208 offset:22528
	ds_read_b128 v[214:217], v208 offset:23552
	global_load_lds_dwordx4 v[192:193], off
	s_add_i32 m0, s58, 0x2000
	s_add_u32 s58, s60, s94
	v_lshl_add_u64 v[204:205], s[60:61], 0, v[174:175]
	s_addc_u32 s59, s61, 0
	s_add_i32 s60, s63, s88
	global_load_lds_dwordx4 v[204:205], off
	v_lshl_add_u64 v[218:219], s[58:59], 0, v[178:179]
	s_mov_b32 m0, s60
	v_lshl_add_u64 v[220:221], s[58:59], 0, v[174:175]
	global_load_lds_dwordx4 v[218:219], off
	s_add_i32 m0, s60, 0x2000
	v_lshl_add_u64 v[2:3], s[8:9], 0, v[176:177]
	global_load_lds_dwordx4 v[220:221], off
	s_mov_b32 m0, s89
	s_nop 0
	global_load_lds_dwordx4 v[2:3], off
	v_lshl_add_u64 v[2:3], s[8:9], 0, v[172:173]
	s_mov_b32 m0, s90
	s_nop 0
	global_load_lds_dwordx4 v[2:3], off
	s_waitcnt vmcnt(8)
	s_waitcnt lgkmcnt(0)
	s_barrier
	s_setprio 1
	s_waitcnt lgkmcnt(0)
	v_mfma_f32_16x16x32_bf16 v[60:63], v[132:135], v[164:167], v[60:63]
	v_mfma_f32_16x16x32_bf16 v[52:55], v[140:143], v[164:167], v[52:55]
	v_mfma_f32_16x16x32_bf16 v[44:47], v[132:135], v[184:187], v[44:47]
	v_mfma_f32_16x16x32_bf16 v[36:39], v[140:143], v[184:187], v[36:39]
	v_mfma_f32_16x16x32_bf16 v[28:31], v[132:135], v[196:199], v[28:31]
	v_mfma_f32_16x16x32_bf16 v[20:23], v[140:143], v[196:199], v[20:23]
	v_mfma_f32_16x16x32_bf16 v[12:15], v[132:135], v[210:213], v[12:15]
	v_mfma_f32_16x16x32_bf16 v[2:5], v[140:143], v[210:213], v[4:7]
	v_mfma_f32_16x16x32_bf16 v[60:63], v[136:139], v[168:171], v[60:63]
	v_mfma_f32_16x16x32_bf16 v[52:55], v[144:147], v[168:171], v[52:55]
	v_mfma_f32_16x16x32_bf16 v[44:47], v[136:139], v[188:191], v[44:47]
	v_mfma_f32_16x16x32_bf16 v[36:39], v[144:147], v[188:191], v[36:39]
	v_mfma_f32_16x16x32_bf16 v[28:31], v[136:139], v[200:203], v[28:31]
	v_mfma_f32_16x16x32_bf16 v[20:23], v[144:147], v[200:203], v[20:23]
	v_mfma_f32_16x16x32_bf16 v[12:15], v[136:139], v[214:217], v[12:15]
	v_mfma_f32_16x16x32_bf16 v[2:5], v[144:147], v[214:217], v[2:5]
	s_setprio 0
	s_setprio 1
	v_mfma_f32_16x16x32_bf16 v[64:67], v[148:151], v[164:167], v[64:67]
	v_mfma_f32_16x16x32_bf16 v[56:59], v[156:159], v[164:167], v[56:59]
	v_mfma_f32_16x16x32_bf16 v[48:51], v[148:151], v[184:187], v[48:51]
	v_mfma_f32_16x16x32_bf16 v[40:43], v[156:159], v[184:187], v[40:43]
	v_mfma_f32_16x16x32_bf16 v[32:35], v[148:151], v[196:199], v[32:35]
	v_mfma_f32_16x16x32_bf16 v[24:27], v[156:159], v[196:199], v[24:27]
	v_mfma_f32_16x16x32_bf16 v[16:19], v[148:151], v[210:213], v[16:19]
	v_mfma_f32_16x16x32_bf16 v[6:9], v[156:159], v[210:213], v[8:11]
	v_mfma_f32_16x16x32_bf16 v[64:67], v[152:155], v[168:171], v[64:67]
	v_mfma_f32_16x16x32_bf16 v[56:59], v[160:163], v[168:171], v[56:59]
	v_mfma_f32_16x16x32_bf16 v[48:51], v[152:155], v[188:191], v[48:51]
	v_mfma_f32_16x16x32_bf16 v[40:43], v[160:163], v[188:191], v[40:43]
	v_mfma_f32_16x16x32_bf16 v[32:35], v[152:155], v[200:203], v[32:35]
	v_mfma_f32_16x16x32_bf16 v[24:27], v[160:163], v[200:203], v[24:27]
	v_mfma_f32_16x16x32_bf16 v[16:19], v[152:155], v[214:217], v[16:19]
	v_mfma_f32_16x16x32_bf16 v[8:11], v[160:163], v[214:217], v[6:9]
	s_setprio 0
	s_barrier
; #define PG8_STAGE(bufoff, gbase, voff) do { _Pragma("unroll") for (int _i = 0; _i < 2; ++_i) \
;         __builtin_amdgcn_global_load_lds((const unsigned*)((const char*)(gbase) + (voff)[_i]), (PG8_LAS unsigned*)(lds + (bufoff) + ldsw + _i * 8192), 16, 0, 0); } while (0)
; #define PG8_LDA(dst, b, h) do { _Pragma("unroll") for (int m = 0; m < 4; ++m) _Pragma("unroll") for (int k = 0; k < 2; ++k) dst[m][k] = *(const PG8_LAS bf16x8*)(lds + PG8_SA(b, h) + aoff + m * 2048 + k * 1024); } while (0)
; #define PG8_LDB(dst, b, h) do { _Pragma("unroll") for (int n = 0; n < 2; ++n) _Pragma("unroll") for (int k = 0; k < 2; ++k) dst[n][k] = *(const PG8_LAS bf16x8*)(lds + PG8_SB(b, h) + boff + n * 2048 + k * 1024); } while (0)
; #define PG8_MMA(ai, bj, At, Bt) do { __builtin_amdgcn_s_setprio(1); _Pragma("unroll") for (int m = 0; m < 4; ++m) _Pragma("unroll") for (int n = 0; n < 2; ++n) _Pragma("unroll") for (int k = 0; k < 2; ++k) \
;         acc[ai][bj][m][n] = __builtin_amdgcn_mfma_f32_16x16x32_bf16(Bt[n][k], At[m][k], acc[ai][bj][m][n], 0, 0, 0); __builtin_amdgcn_s_setprio(0); } while (0)
; #define PG8_WAIT_V(n) asm volatile("s_waitcnt vmcnt(" #n ")" ::: "memory")
; #define PG8_WAIT_L(n) asm volatile("s_waitcnt lgkmcnt(" #n ")" ::: "memory")
; #define PG8_BAR __builtin_amdgcn_s_barrier()
; #define PG8_SCHED __builtin_amdgcn_sched_barrier(0)
; template <class Epi, class Sched, bool ALIGN_EPI = false, bool SP2 = false>
; __device__ __forceinline__ void gemm_phase(PG8_LAS unsigned char* lds, const Gemm g, const Sched& S, const Epi& E, int tid_in) {
;     ...
;             PG8_LDB(B0, 1, 0); PG8_LDB(B1, 1, 1); PG8_SCHED; PG8_LDA(At, 1, 0); PG8_STAGE(PG8_SA(0, 1), a2 + hstepA, voffA);
;             PG8_WAIT_V(8); PG8_WAIT_L(0); PG8_BAR; PG8_MMA(0, 0, At, B0); PG8_MMA(0, 1, At, B1); PG8_BAR; PG8_SCHED;
	s_add_i32 s58, 0, 0x18000
	v_add_u32_e32 v0, s58, v207
	s_add_i32 s59, 0, 0x1c000
	ds_read_b128 v[132:135], v0
	ds_read_b128 v[136:139], v0 offset:1024
	ds_read_b128 v[140:143], v0 offset:2048
	ds_read_b128 v[144:147], v0 offset:3072
	v_add_u32_e32 v0, s59, v207
	ds_read_b128 v[148:151], v0
	ds_read_b128 v[152:155], v0 offset:1024
	ds_read_b128 v[156:159], v0 offset:2048
	ds_read_b128 v[160:163], v0 offset:3072
	s_add_u32 s8, s8, s94
	s_addc_u32 s9, s9, 0
	s_mov_b32 m0, s91
	v_lshl_add_u64 v[6:7], s[8:9], 0, v[176:177]
	ds_read_b128 v[164:167], v208 offset:32768
	ds_read_b128 v[168:171], v208 offset:33792
	ds_read_b128 v[184:187], v208 offset:34816
	ds_read_b128 v[188:191], v208 offset:35840
	ds_read_b128 v[196:199], v208 offset:36864
	ds_read_b128 v[200:203], v208 offset:37888
	ds_read_b128 v[210:213], v208 offset:38912
	ds_read_b128 v[214:217], v208 offset:39936
	global_load_lds_dwordx4 v[6:7], off
	v_lshl_add_u64 v[6:7], s[8:9], 0, v[172:173]
	s_mov_b32 m0, s92
	s_nop 0
	global_load_lds_dwordx4 v[6:7], off
	s_waitcnt vmcnt(8)
	s_waitcnt lgkmcnt(0)
	s_barrier
	s_setprio 1
	s_waitcnt lgkmcnt(0)
	v_mfma_f32_16x16x32_bf16 v[124:127], v[132:135], v[164:167], v[124:127]
	v_mfma_f32_16x16x32_bf16 v[116:119], v[140:143], v[164:167], v[116:119]
	v_mfma_f32_16x16x32_bf16 v[108:111], v[132:135], v[184:187], v[108:111]
	v_mfma_f32_16x16x32_bf16 v[100:103], v[140:143], v[184:187], v[100:103]
	v_mfma_f32_16x16x32_bf16 v[92:95], v[132:135], v[196:199], v[92:95]
	v_mfma_f32_16x16x32_bf16 v[84:87], v[140:143], v[196:199], v[84:87]
	v_mfma_f32_16x16x32_bf16 v[76:79], v[132:135], v[210:213], v[76:79]
	v_mfma_f32_16x16x32_bf16 v[68:71], v[140:143], v[210:213], v[68:71]
	v_mfma_f32_16x16x32_bf16 v[124:127], v[136:139], v[168:171], v[124:127]
	v_mfma_f32_16x16x32_bf16 v[116:119], v[144:147], v[168:171], v[116:119]
	v_mfma_f32_16x16x32_bf16 v[108:111], v[136:139], v[188:191], v[108:111]
	v_mfma_f32_16x16x32_bf16 v[100:103], v[144:147], v[188:191], v[100:103]
	v_mfma_f32_16x16x32_bf16 v[92:95], v[136:139], v[200:203], v[92:95]
	v_mfma_f32_16x16x32_bf16 v[84:87], v[144:147], v[200:203], v[84:87]
	v_mfma_f32_16x16x32_bf16 v[76:79], v[136:139], v[214:217], v[76:79]
	v_mfma_f32_16x16x32_bf16 v[68:71], v[144:147], v[214:217], v[68:71]
	s_setprio 0
	s_setprio 1
	v_mfma_f32_16x16x32_bf16 v[128:131], v[148:151], v[164:167], v[128:131]
	v_mfma_f32_16x16x32_bf16 v[120:123], v[156:159], v[164:167], v[120:123]
	v_mfma_f32_16x16x32_bf16 v[112:115], v[148:151], v[184:187], v[112:115]
	v_mfma_f32_16x16x32_bf16 v[104:107], v[156:159], v[184:187], v[104:107]
	v_mfma_f32_16x16x32_bf16 v[96:99], v[148:151], v[196:199], v[96:99]
	v_mfma_f32_16x16x32_bf16 v[88:91], v[156:159], v[196:199], v[88:91]
	v_mfma_f32_16x16x32_bf16 v[80:83], v[148:151], v[210:213], v[80:83]
	v_mfma_f32_16x16x32_bf16 v[72:75], v[156:159], v[210:213], v[72:75]
	v_mfma_f32_16x16x32_bf16 v[128:131], v[152:155], v[168:171], v[128:131]
	v_mfma_f32_16x16x32_bf16 v[120:123], v[160:163], v[168:171], v[120:123]
	v_mfma_f32_16x16x32_bf16 v[112:115], v[152:155], v[188:191], v[112:115]
	v_mfma_f32_16x16x32_bf16 v[104:107], v[160:163], v[188:191], v[104:107]
	v_mfma_f32_16x16x32_bf16 v[96:99], v[152:155], v[200:203], v[96:99]
	v_mfma_f32_16x16x32_bf16 v[88:91], v[160:163], v[200:203], v[88:91]
	v_mfma_f32_16x16x32_bf16 v[80:83], v[152:155], v[214:217], v[80:83]
	v_mfma_f32_16x16x32_bf16 v[72:75], v[160:163], v[214:217], v[72:75]
	s_setprio 0
	s_barrier
; #define PG8_STAGE(bufoff, gbase, voff) do { _Pragma("unroll") for (int _i = 0; _i < 2; ++_i) \
;         __builtin_amdgcn_global_load_lds((const unsigned*)((const char*)(gbase) + (voff)[_i]), (PG8_LAS unsigned*)(lds + (bufoff) + ldsw + _i * 8192), 16, 0, 0); } while (0)
; #define PG8_LDA(dst, b, h) do { _Pragma("unroll") for (int m = 0; m < 4; ++m) _Pragma("unroll") for (int k = 0; k < 2; ++k) dst[m][k] = *(const PG8_LAS bf16x8*)(lds + PG8_SA(b, h) + aoff + m * 2048 + k * 1024); } while (0)
; #define PG8_MMA(ai, bj, At, Bt) do { __builtin_amdgcn_s_setprio(1); _Pragma("unroll") for (int m = 0; m < 4; ++m) _Pragma("unroll") for (int n = 0; n < 2; ++n) _Pragma("unroll") for (int k = 0; k < 2; ++k) \
;         acc[ai][bj][m][n] = __builtin_amdgcn_mfma_f32_16x16x32_bf16(Bt[n][k], At[m][k], acc[ai][bj][m][n], 0, 0, 0); __builtin_amdgcn_s_setprio(0); } while (0)
; #define PG8_WAIT_V(n) asm volatile("s_waitcnt vmcnt(" #n ")" ::: "memory")
; #define PG8_WAIT_L(n) asm volatile("s_waitcnt lgkmcnt(" #n ")" ::: "memory")
; #define PG8_BAR __builtin_amdgcn_s_barrier()
; #define PG8_SCHED __builtin_amdgcn_sched_barrier(0)
; template <class Epi, class Sched, bool ALIGN_EPI = false, bool SP2 = false>
; __device__ __forceinline__ void gemm_phase(PG8_LAS unsigned char* lds, const Gemm g, const Sched& S, const Epi& E, int tid_in) {
;     ...
;             PG8_LDA(At, 1, 1); PG8_STAGE(PG8_SB(1, 0), b3, voffB); PG8_STAGE(PG8_SB(1, 1), b3 + hstep, voffB); PG8_STAGE(PG8_SA(1, 0), a3, voffA);
;             PG8_WAIT_V(8); PG8_WAIT_L(0); PG8_BAR; PG8_MMA(1, 0, At, B0); PG8_MMA(1, 1, At, B1); PG8_BAR; PG8_SCHED;
;     ...
;         }
;         if constexpr (ALIGN_EPI) { if (wr == 0) PG8_BAR; }
	s_add_i32 s8, s58, s88
	v_lshl_add_u64 v[6:7], v[192:193], 0, s[96:97]
	s_mov_b32 m0, s8
	ds_read_b128 v[164:167], v208 offset:49152
	ds_read_b128 v[168:171], v208 offset:50176
	ds_read_b128 v[184:187], v208 offset:51200
	ds_read_b128 v[188:191], v208 offset:52224
	ds_read_b128 v[196:199], v208 offset:53248
	ds_read_b128 v[200:203], v208 offset:54272
	ds_read_b128 v[210:213], v208 offset:55296
	ds_read_b128 v[214:217], v208 offset:56320
	global_load_lds_dwordx4 v[6:7], off
	v_lshl_add_u64 v[6:7], v[204:205], 0, s[96:97]
	s_add_i32 m0, s8, 0x2000
	s_add_i32 s8, s59, s88
	global_load_lds_dwordx4 v[6:7], off
	v_lshl_add_u64 v[6:7], v[218:219], 0, s[96:97]
	s_mov_b32 m0, s8
	s_nop 0
	global_load_lds_dwordx4 v[6:7], off
	v_lshl_add_u64 v[6:7], v[220:221], 0, s[96:97]
	s_add_i32 m0, s8, 0x2000
	s_nop 0
	global_load_lds_dwordx4 v[6:7], off
	v_lshl_add_u64 v[6:7], s[0:1], 0, v[176:177]
	s_mov_b32 m0, s93
	s_nop 0
	global_load_lds_dwordx4 v[6:7], off
	v_lshl_add_u64 v[6:7], s[0:1], 0, v[172:173]
	s_mov_b32 m0, s78
	s_nop 0
	global_load_lds_dwordx4 v[6:7], off
	s_waitcnt vmcnt(8)
	s_waitcnt lgkmcnt(0)
	s_barrier
	s_setprio 1
	s_waitcnt lgkmcnt(0)
	v_mfma_f32_16x16x32_bf16 v[60:63], v[132:135], v[164:167], v[60:63]
	v_mfma_f32_16x16x32_bf16 v[52:55], v[140:143], v[164:167], v[52:55]
	v_mfma_f32_16x16x32_bf16 v[44:47], v[132:135], v[184:187], v[44:47]
	v_mfma_f32_16x16x32_bf16 v[36:39], v[140:143], v[184:187], v[36:39]
	v_mfma_f32_16x16x32_bf16 v[28:31], v[132:135], v[196:199], v[28:31]
	v_mfma_f32_16x16x32_bf16 v[20:23], v[140:143], v[196:199], v[20:23]
	v_mfma_f32_16x16x32_bf16 v[12:15], v[132:135], v[210:213], v[12:15]
	v_mfma_f32_16x16x32_bf16 v[2:5], v[140:143], v[210:213], v[2:5]
	v_mfma_f32_16x16x32_bf16 v[60:63], v[136:139], v[168:171], v[60:63]
	v_mfma_f32_16x16x32_bf16 v[52:55], v[144:147], v[168:171], v[52:55]
	v_mfma_f32_16x16x32_bf16 v[44:47], v[136:139], v[188:191], v[44:47]
	v_mfma_f32_16x16x32_bf16 v[36:39], v[144:147], v[188:191], v[36:39]
	v_mfma_f32_16x16x32_bf16 v[28:31], v[136:139], v[200:203], v[28:31]
	v_mfma_f32_16x16x32_bf16 v[20:23], v[144:147], v[200:203], v[20:23]
	v_mfma_f32_16x16x32_bf16 v[12:15], v[136:139], v[214:217], v[12:15]
	v_mfma_f32_16x16x32_bf16 v[4:7], v[144:147], v[214:217], v[2:5]
	s_setprio 0
	s_setprio 1
	v_mfma_f32_16x16x32_bf16 v[64:67], v[148:151], v[164:167], v[64:67]
	v_mfma_f32_16x16x32_bf16 v[56:59], v[156:159], v[164:167], v[56:59]
	v_mfma_f32_16x16x32_bf16 v[48:51], v[148:151], v[184:187], v[48:51]
	v_mfma_f32_16x16x32_bf16 v[40:43], v[156:159], v[184:187], v[40:43]
	v_mfma_f32_16x16x32_bf16 v[32:35], v[148:151], v[196:199], v[32:35]
	v_mfma_f32_16x16x32_bf16 v[24:27], v[156:159], v[196:199], v[24:27]
	v_mfma_f32_16x16x32_bf16 v[16:19], v[148:151], v[210:213], v[16:19]
	v_mfma_f32_16x16x32_bf16 v[8:11], v[156:159], v[210:213], v[8:11]
	v_mfma_f32_16x16x32_bf16 v[64:67], v[152:155], v[168:171], v[64:67]
	v_mfma_f32_16x16x32_bf16 v[56:59], v[160:163], v[168:171], v[56:59]
	v_mfma_f32_16x16x32_bf16 v[48:51], v[152:155], v[188:191], v[48:51]
	v_mfma_f32_16x16x32_bf16 v[40:43], v[160:163], v[188:191], v[40:43]
	v_mfma_f32_16x16x32_bf16 v[32:35], v[152:155], v[200:203], v[32:35]
	v_mfma_f32_16x16x32_bf16 v[24:27], v[160:163], v[200:203], v[24:27]
	v_mfma_f32_16x16x32_bf16 v[16:19], v[152:155], v[214:217], v[16:19]
	v_mfma_f32_16x16x32_bf16 v[8:11], v[160:163], v[214:217], v[8:11]
	s_setprio 0
	s_barrier
	s_add_u32 s6, s6, 0x100
	s_addc_u32 s7, s7, 0
	s_add_u32 s54, s54, 0x100
	s_addc_u32 s55, s55, 0
	s_add_i32 s56, s56, -2
	s_cmp_ge_u32 s57, s18
	s_mov_b32 s0, s57
	s_cbranch_scc0 .LBB0_1180
	s_and_b64 vcc, exec, s[76:77]
	s_cbranch_vccz .LBB0_1183
	s_barrier
